# attention: compute segment of each KV step runs at s_setprio 1 (reset before the barrier), on top of deferred row-max check
# baseline (speedup 1.0000x reference)
; __device__ __forceinline__ void pv3(f32x16* o, const s16x4* vf, bf16x8 pa0, bf16x8 pa1, bf16x8 pa2, bf16x8 pa3) {
;     ...
;   o[0] = __builtin_amdgcn_mfma_f32_32x32x16_bf16(pa0, PKV(0), o[0], 0, 0, 0);
;   o[1] = __builtin_amdgcn_mfma_f32_32x32x16_bf16(pa0, PKV(8), o[1], 0, 0, 0);
;   o[0] = __builtin_amdgcn_mfma_f32_32x32x16_bf16(pa1, PKV(2), o[0], 0, 0, 0);
;   o[1] = __builtin_amdgcn_mfma_f32_32x32x16_bf16(pa1, PKV(10), o[1], 0, 0, 0);
;   o[0] = __builtin_amdgcn_mfma_f32_32x32x16_bf16(pa2, PKV(4), o[0], 0, 0, 0);
;   o[1] = __builtin_amdgcn_mfma_f32_32x32x16_bf16(pa2, PKV(12), o[1], 0, 0, 0);
;   o[0] = __builtin_amdgcn_mfma_f32_32x32x16_bf16(pa3, PKV(6), o[0], 0, 0, 0);
;   o[1] = __builtin_amdgcn_mfma_f32_32x32x16_bf16(pa3, PKV(14), o[1], 0, 0, 0);
;     ...
; }
.Lwd_a:
	s_barrier
	s_waitcnt lgkmcnt(0)
	s_setprio 1
	v_mfma_f32_32x32x16_bf16 v[80:95], v[246:249], v[248:251], 0
	v_exp_f32_e32 v64, v64
	v_add_f32_e32 v213, v32, v213
	ds_read_b64_tr_b16 v[148:149], v217 offset:0
	v_exp_f32_e32 v65, v65
	v_add_f32_e32 v213, v33, v213
	ds_read_b64_tr_b16 v[150:151], v217 offset:512
	v_mfma_f32_32x32x16_bf16 v[80:95], v[48:51], v[116:119], v[80:95]
	v_exp_f32_e32 v66, v66
	v_add_f32_e32 v213, v34, v213
	ds_read_b64_tr_b16 v[140:141], v217 offset:1024
	v_exp_f32_e32 v67, v67
	v_add_f32_e32 v213, v35, v213
	ds_read_b64_tr_b16 v[142:143], v217 offset:1536
	v_mfma_f32_32x32x16_bf16 v[48:63], v[52:55], v[116:119], 0
	v_exp_f32_e32 v68, v68
	v_add_f32_e32 v213, v36, v213
	ds_read_b64_tr_b16 v[132:133], v217 offset:2048
	v_exp_f32_e32 v69, v69
	v_add_f32_e32 v213, v37, v213
	ds_read_b64_tr_b16 v[134:135], v217 offset:2560
	v_mfma_f32_32x32x16_bf16 v[48:63], v[246:249], v[248:251], v[48:63]
	v_exp_f32_e32 v70, v70
	v_add_f32_e32 v213, v38, v213
	ds_read_b64_tr_b16 v[124:125], v217 offset:3072
	v_exp_f32_e32 v71, v71
	v_add_f32_e32 v213, v39, v213
	ds_read_b64_tr_b16 v[126:127], v217 offset:3584
	v_mfma_f32_32x32x16_bf16 v[80:95], v[188:191], v[112:115], v[80:95]
	v_exp_f32_e32 v72, v72
	v_add_f32_e32 v213, v40, v213
	ds_read_b64_tr_b16 v[144:145], v217 offset:4096
	v_exp_f32_e32 v73, v73
	v_add_f32_e32 v213, v41, v213
	ds_read_b64_tr_b16 v[146:147], v217 offset:4608
	v_mfma_f32_32x32x16_bf16 v[48:63], v[184:187], v[112:115], v[48:63]
	v_exp_f32_e32 v74, v74
	v_add_f32_e32 v213, v42, v213
	ds_read_b64_tr_b16 v[136:137], v217 offset:5120
	v_exp_f32_e32 v75, v75
	v_add_f32_e32 v213, v43, v213
	ds_read_b64_tr_b16 v[138:139], v217 offset:5632
	v_mfma_f32_32x32x16_bf16 v[80:95], v[180:183], v[108:111], v[80:95]
	v_exp_f32_e32 v76, v76
	v_add_f32_e32 v213, v44, v213
	ds_read_b64_tr_b16 v[128:129], v217 offset:6144
	v_exp_f32_e32 v77, v77
	v_add_f32_e32 v213, v45, v213
	ds_read_b64_tr_b16 v[130:131], v217 offset:6656
	v_mfma_f32_32x32x16_bf16 v[48:63], v[176:179], v[108:111], v[48:63]
	v_exp_f32_e32 v78, v78
	v_add_f32_e32 v213, v46, v213
	ds_read_b64_tr_b16 v[120:121], v217 offset:7168
	v_exp_f32_e32 v79, v79
	v_add_f32_e32 v213, v47, v213
	ds_read_b64_tr_b16 v[122:123], v217 offset:7680
	v_mfma_f32_32x32x16_bf16 v[80:95], v[172:175], v[104:107], v[80:95]
	v_add_f32_e32 v245, v64, v65
	v_add_f32_e32 v245, v66, v245
	v_add_f32_e32 v245, v67, v245
	v_add_f32_e32 v245, v68, v245
	v_add_f32_e32 v245, v69, v245
	v_add_f32_e32 v245, v70, v245
	v_mfma_f32_32x32x16_bf16 v[48:63], v[168:171], v[104:107], v[48:63]
	v_add_f32_e32 v245, v71, v245
	v_add_f32_e32 v245, v72, v245
	v_add_f32_e32 v245, v73, v245
	v_add_f32_e32 v245, v74, v245
	v_add_f32_e32 v245, v75, v245
	v_mfma_f32_32x32x16_bf16 v[80:95], v[164:167], v[100:103], v[80:95]
	v_add_f32_e32 v245, v76, v245
	v_add_f32_e32 v245, v77, v245
	v_add_f32_e32 v245, v78, v245
	v_add_f32_e32 v245, v79, v245
	v_add_f32_e32 v213, v245, v213
	v_mfma_f32_32x32x16_bf16 v[48:63], v[160:163], v[100:103], v[48:63]
	v_cvt_pk_bf16_f32 v32, v32, v33
	v_cvt_pk_bf16_f32 v33, v34, v35
	v_cvt_pk_bf16_f32 v34, v36, v37
	v_cvt_pk_bf16_f32 v35, v38, v39
	v_cvt_pk_bf16_f32 v36, v40, v41
	v_cvt_pk_bf16_f32 v37, v42, v43
	v_mfma_f32_32x32x16_bf16 v[80:95], v[156:159], v[96:99], v[80:95]
	v_cvt_pk_bf16_f32 v38, v44, v45
	v_cvt_pk_bf16_f32 v39, v46, v47
	v_cvt_pk_bf16_f32 v64, v64, v65
	v_cvt_pk_bf16_f32 v65, v66, v67
	v_cvt_pk_bf16_f32 v66, v68, v69
	v_cvt_pk_bf16_f32 v67, v70, v71
	v_mfma_f32_32x32x16_bf16 v[48:63], v[152:155], v[96:99], v[48:63]
	v_cvt_pk_bf16_f32 v68, v72, v73
	v_cvt_pk_bf16_f32 v69, v74, v75
	v_cvt_pk_bf16_f32 v70, v76, v77
	v_cvt_pk_bf16_f32 v71, v78, v79
	s_waitcnt lgkmcnt(0)
	v_mfma_f32_32x32x16_bf16 v[0:15], v[32:35], v[148:151], v[0:15]
	v_exp_f32_e32 v40, v88
	v_exp_f32_e32 v41, v89
	v_mfma_f32_32x32x16_bf16 v[16:31], v[32:35], v[144:147], v[16:31]
	v_exp_f32_e32 v42, v90
	v_exp_f32_e32 v43, v91
	v_mfma_f32_32x32x16_bf16 v[0:15], v[36:39], v[140:143], v[0:15]
	v_exp_f32_e32 v44, v92
	v_exp_f32_e32 v45, v93
	v_mfma_f32_32x32x16_bf16 v[16:31], v[36:39], v[136:139], v[16:31]
	v_exp_f32_e32 v46, v94
	v_exp_f32_e32 v47, v95
	v_mfma_f32_32x32x16_bf16 v[0:15], v[64:67], v[132:135], v[0:15]
	v_exp_f32_e32 v32, v80
	v_exp_f32_e32 v33, v81
	v_mfma_f32_32x32x16_bf16 v[16:31], v[64:67], v[128:131], v[16:31]
	v_exp_f32_e32 v34, v82
	v_exp_f32_e32 v35, v83
	v_mfma_f32_32x32x16_bf16 v[0:15], v[68:71], v[124:127], v[0:15]
	v_exp_f32_e32 v36, v84
	v_exp_f32_e32 v37, v85
	v_mfma_f32_32x32x16_bf16 v[16:31], v[68:71], v[120:123], v[16:31]
	v_exp_f32_e32 v38, v86
	v_exp_f32_e32 v39, v87
	s_setprio 0
	s_barrier
	v_max3_f32 v252, v80, v81, v82
	v_max3_f32 v252, v252, v83, v84
	v_max3_f32 v252, v252, v85, v86
	v_max3_f32 v252, v252, v87, v88
	v_max3_f32 v252, v252, v89, v90
	v_max3_f32 v252, v252, v91, v92
	v_max3_f32 v252, v252, v93, v94
	v_max3_f32 v252, v252, v95, v48
	v_max3_f32 v252, v252, v49, v50
	v_max3_f32 v252, v252, v51, v52
	v_max3_f32 v252, v252, v53, v54
	v_max3_f32 v252, v252, v55, v56
	v_max3_f32 v252, v252, v57, v58
	v_max3_f32 v252, v252, v59, v60
	v_max3_f32 v252, v252, v61, v62
	v_max_f32_e32 v252, v252, v63
	v_cmp_nge_f32_e32 vcc, s23, v252
	s_nop 3
	s_cmp_lg_u64 vcc, 0
	s_cbranch_scc1 .Lrare_a

; template <int MODE> __device__ __forceinline__ void attn_unit(const bf16_t* __restrict__ Q, const bf16_t* __restrict__ KV, const bf16_t* __restrict__ KR, bf16_t* __restrict__ O,
;                                           long rowbase, int q0, int h, LAS char* lds) {
;     ...
;   for (int j = 1; j + 1 < NT; j += 2) {
;     STEP(j, pB0, pB1, mnB, alB, pA0, pA1, alA);
;     STEP(j + 1, pA0, pA1, mnA, alA, pB0, pB1, alB);
;   }
.Lwd_b:
	s_barrier
	s_waitcnt lgkmcnt(0)
	s_setprio 1
	v_mfma_f32_32x32x16_bf16 v[80:95], v[246:249], v[248:251], 0
	v_exp_f32_e32 v48, v48
	v_add_f32_e32 v213, v32, v213
	ds_read_b64_tr_b16 v[148:149], v217 offset:0
	v_exp_f32_e32 v49, v49
	v_add_f32_e32 v213, v33, v213
	ds_read_b64_tr_b16 v[150:151], v217 offset:512
	v_mfma_f32_32x32x16_bf16 v[80:95], v[64:67], v[116:119], v[80:95]
	v_exp_f32_e32 v50, v50
	v_add_f32_e32 v213, v34, v213
	ds_read_b64_tr_b16 v[140:141], v217 offset:1024
	v_exp_f32_e32 v51, v51
	v_add_f32_e32 v213, v35, v213
	ds_read_b64_tr_b16 v[142:143], v217 offset:1536
	v_mfma_f32_32x32x16_bf16 v[64:79], v[68:71], v[116:119], 0
	v_exp_f32_e32 v52, v52
	v_add_f32_e32 v213, v36, v213
	ds_read_b64_tr_b16 v[132:133], v217 offset:2048
	v_exp_f32_e32 v53, v53
	v_add_f32_e32 v213, v37, v213
	ds_read_b64_tr_b16 v[134:135], v217 offset:2560
	v_mfma_f32_32x32x16_bf16 v[64:79], v[246:249], v[248:251], v[64:79]
	v_exp_f32_e32 v54, v54
	v_add_f32_e32 v213, v38, v213
	ds_read_b64_tr_b16 v[124:125], v217 offset:3072
	v_exp_f32_e32 v55, v55
	v_add_f32_e32 v213, v39, v213
	ds_read_b64_tr_b16 v[126:127], v217 offset:3584
	v_mfma_f32_32x32x16_bf16 v[80:95], v[188:191], v[112:115], v[80:95]
	v_exp_f32_e32 v56, v56
	v_add_f32_e32 v213, v40, v213
	ds_read_b64_tr_b16 v[144:145], v217 offset:4096
	v_exp_f32_e32 v57, v57
	v_add_f32_e32 v213, v41, v213
	ds_read_b64_tr_b16 v[146:147], v217 offset:4608
	v_mfma_f32_32x32x16_bf16 v[64:79], v[184:187], v[112:115], v[64:79]
	v_exp_f32_e32 v58, v58
	v_add_f32_e32 v213, v42, v213
	ds_read_b64_tr_b16 v[136:137], v217 offset:5120
	v_exp_f32_e32 v59, v59
	v_add_f32_e32 v213, v43, v213
	ds_read_b64_tr_b16 v[138:139], v217 offset:5632
	v_mfma_f32_32x32x16_bf16 v[80:95], v[180:183], v[108:111], v[80:95]
	v_exp_f32_e32 v60, v60
	v_add_f32_e32 v213, v44, v213
	ds_read_b64_tr_b16 v[128:129], v217 offset:6144
	v_exp_f32_e32 v61, v61
	v_add_f32_e32 v213, v45, v213
	ds_read_b64_tr_b16 v[130:131], v217 offset:6656
	v_mfma_f32_32x32x16_bf16 v[64:79], v[176:179], v[108:111], v[64:79]
	v_exp_f32_e32 v62, v62
	v_add_f32_e32 v213, v46, v213
	ds_read_b64_tr_b16 v[120:121], v217 offset:7168
	v_exp_f32_e32 v63, v63
	v_add_f32_e32 v213, v47, v213
	ds_read_b64_tr_b16 v[122:123], v217 offset:7680
	v_mfma_f32_32x32x16_bf16 v[80:95], v[172:175], v[104:107], v[80:95]
	v_add_f32_e32 v245, v48, v49
	v_add_f32_e32 v245, v50, v245
	v_add_f32_e32 v245, v51, v245
	v_add_f32_e32 v245, v52, v245
	v_add_f32_e32 v245, v53, v245
	v_add_f32_e32 v245, v54, v245
	v_mfma_f32_32x32x16_bf16 v[64:79], v[168:171], v[104:107], v[64:79]
	v_add_f32_e32 v245, v55, v245
	v_add_f32_e32 v245, v56, v245
	v_add_f32_e32 v245, v57, v245
	v_add_f32_e32 v245, v58, v245
	v_add_f32_e32 v245, v59, v245
	v_mfma_f32_32x32x16_bf16 v[80:95], v[164:167], v[100:103], v[80:95]
	v_add_f32_e32 v245, v60, v245
	v_add_f32_e32 v245, v61, v245
	v_add_f32_e32 v245, v62, v245
	v_add_f32_e32 v245, v63, v245
	v_add_f32_e32 v213, v245, v213
	v_mfma_f32_32x32x16_bf16 v[64:79], v[160:163], v[100:103], v[64:79]
	v_cvt_pk_bf16_f32 v32, v32, v33
	v_cvt_pk_bf16_f32 v33, v34, v35
	v_cvt_pk_bf16_f32 v34, v36, v37
	v_cvt_pk_bf16_f32 v35, v38, v39
	v_cvt_pk_bf16_f32 v36, v40, v41
	v_cvt_pk_bf16_f32 v37, v42, v43
	v_mfma_f32_32x32x16_bf16 v[80:95], v[156:159], v[96:99], v[80:95]
	v_cvt_pk_bf16_f32 v38, v44, v45
	v_cvt_pk_bf16_f32 v39, v46, v47
	v_cvt_pk_bf16_f32 v48, v48, v49
	v_cvt_pk_bf16_f32 v49, v50, v51
	v_cvt_pk_bf16_f32 v50, v52, v53
	v_cvt_pk_bf16_f32 v51, v54, v55
	v_mfma_f32_32x32x16_bf16 v[64:79], v[152:155], v[96:99], v[64:79]
	v_cvt_pk_bf16_f32 v52, v56, v57
	v_cvt_pk_bf16_f32 v53, v58, v59
	v_cvt_pk_bf16_f32 v54, v60, v61
	v_cvt_pk_bf16_f32 v55, v62, v63
	s_waitcnt lgkmcnt(0)
	v_mfma_f32_32x32x16_bf16 v[0:15], v[32:35], v[148:151], v[0:15]
	v_exp_f32_e32 v40, v88
	v_exp_f32_e32 v41, v89
	v_mfma_f32_32x32x16_bf16 v[16:31], v[32:35], v[144:147], v[16:31]
	v_exp_f32_e32 v42, v90
	v_exp_f32_e32 v43, v91
	v_mfma_f32_32x32x16_bf16 v[0:15], v[36:39], v[140:143], v[0:15]
	v_exp_f32_e32 v44, v92
	v_exp_f32_e32 v45, v93
	v_mfma_f32_32x32x16_bf16 v[16:31], v[36:39], v[136:139], v[16:31]
	v_exp_f32_e32 v46, v94
	v_exp_f32_e32 v47, v95
	v_mfma_f32_32x32x16_bf16 v[0:15], v[48:51], v[132:135], v[0:15]
	v_exp_f32_e32 v32, v80
	v_exp_f32_e32 v33, v81
	v_mfma_f32_32x32x16_bf16 v[16:31], v[48:51], v[128:131], v[16:31]
	v_exp_f32_e32 v34, v82
	v_exp_f32_e32 v35, v83
	v_mfma_f32_32x32x16_bf16 v[0:15], v[52:55], v[124:127], v[0:15]
	v_exp_f32_e32 v36, v84
	v_exp_f32_e32 v37, v85
	v_mfma_f32_32x32x16_bf16 v[16:31], v[52:55], v[120:123], v[16:31]
	v_exp_f32_e32 v38, v86
	v_exp_f32_e32 v39, v87
	s_setprio 0
	s_add_i32 s6, s6, 2
	s_barrier
	s_addk_i32 s63, 0x4000
	v_lshl_add_u64 v[220:221], v[220:221], 0, s[12:13]
	v_lshl_add_u64 v[222:223], v[222:223], 0, s[10:11]
	v_lshl_add_u64 v[224:225], v[224:225], 0, s[10:11]
	s_and_b64 vcc, exec, s[58:59]
	s_cbranch_vccnz .LBB0_597
	s_mov_b32 s68, s70
	s_mov_b32 s70, s71
	s_branch .LBB0_570

; #define SBAR() __builtin_amdgcn_sched_barrier(0)
; #define BAR() do { SBAR(); __builtin_amdgcn_s_barrier(); asm volatile("" ::: "memory"); SBAR(); } while (0)
; __device__ __forceinline__ void pv3(f32x16* o, const s16x4* vf, bf16x8 pa0, bf16x8 pa1, bf16x8 pa2, bf16x8 pa3) {
;     ...
;   o[0] = __builtin_amdgcn_mfma_f32_32x32x16_bf16(pa0, PKV(0), o[0], 0, 0, 0);
;   o[1] = __builtin_amdgcn_mfma_f32_32x32x16_bf16(pa0, PKV(8), o[1], 0, 0, 0);
;   o[0] = __builtin_amdgcn_mfma_f32_32x32x16_bf16(pa1, PKV(2), o[0], 0, 0, 0);
;   o[1] = __builtin_amdgcn_mfma_f32_32x32x16_bf16(pa1, PKV(10), o[1], 0, 0, 0);
;   o[0] = __builtin_amdgcn_mfma_f32_32x32x16_bf16(pa2, PKV(4), o[0], 0, 0, 0);
;   o[1] = __builtin_amdgcn_mfma_f32_32x32x16_bf16(pa2, PKV(12), o[1], 0, 0, 0);
;   o[0] = __builtin_amdgcn_mfma_f32_32x32x16_bf16(pa3, PKV(6), o[0], 0, 0, 0);
;   o[1] = __builtin_amdgcn_mfma_f32_32x32x16_bf16(pa3, PKV(14), o[1], 0, 0, 0);
;     ...
; }
; template <int MODE> __device__ __forceinline__ void attn_unit(const bf16_t* __restrict__ Q, const bf16_t* __restrict__ KV, const bf16_t* __restrict__ KR, bf16_t* __restrict__ O,
;                                           long rowbase, int q0, int h, LAS char* lds) {
;     ...
;   STEP(NT - 1, pB0, pB1, mnB, alB, pA0, pA1, alA);
;   if (wid < 4) BAR();
;   finishSM2(pB0, pB1, alB, l_reg, pa0, pa1, pa2, pa3); SBAR();
;   vload16(vf, vbase + ((NT - 1) & 3) * VSLOT); asm volatile("s_waitcnt lgkmcnt(0)" ::: "memory"); SBAR();
;   pv3(o, vf, pa0, pa1, pa2, pa3);
.Ljoin_u:
	ds_read_b128 v[48:51], v231 offset:36864
	ds_read_b128 v[52:55], v231 offset:37376
	ds_read_b128 v[188:191], v231 offset:38912
	ds_read_b128 v[184:187], v231 offset:39424
	ds_read_b128 v[180:183], v231 offset:40960
	ds_read_b128 v[176:179], v231 offset:41472
	ds_read_b128 v[172:175], v231 offset:43008
	ds_read_b128 v[168:171], v231 offset:43520
	ds_read_b128 v[164:167], v231 offset:45056
	ds_read_b128 v[160:163], v231 offset:45568
	ds_read_b128 v[156:159], v231 offset:47104
	ds_read_b128 v[152:155], v231 offset:47616
	s_waitcnt vmcnt(0) lgkmcnt(0)
	s_barrier
	s_waitcnt lgkmcnt(0)
	s_setprio 1
	v_mfma_f32_32x32x16_bf16 v[80:95], v[246:249], v[248:251], 0
	v_exp_f32_e32 v64, v64
	v_add_f32_e32 v213, v32, v213
	ds_read_b64_tr_b16 v[148:149], v233 offset:0
	v_exp_f32_e32 v65, v65
	v_add_f32_e32 v213, v33, v213
	ds_read_b64_tr_b16 v[150:151], v233 offset:512
	v_mfma_f32_32x32x16_bf16 v[80:95], v[48:51], v[116:119], v[80:95]
	v_exp_f32_e32 v66, v66
	v_add_f32_e32 v213, v34, v213
	ds_read_b64_tr_b16 v[140:141], v233 offset:1024
	v_exp_f32_e32 v67, v67
	v_add_f32_e32 v213, v35, v213
	ds_read_b64_tr_b16 v[142:143], v233 offset:1536
	v_mfma_f32_32x32x16_bf16 v[48:63], v[52:55], v[116:119], 0
	v_exp_f32_e32 v68, v68
	v_add_f32_e32 v213, v36, v213
	ds_read_b64_tr_b16 v[132:133], v233 offset:2048
	v_exp_f32_e32 v69, v69
	v_add_f32_e32 v213, v37, v213
	ds_read_b64_tr_b16 v[134:135], v233 offset:2560
	v_mfma_f32_32x32x16_bf16 v[48:63], v[246:249], v[248:251], v[48:63]
	v_exp_f32_e32 v70, v70
	v_add_f32_e32 v213, v38, v213
	ds_read_b64_tr_b16 v[124:125], v233 offset:3072
	v_exp_f32_e32 v71, v71
	v_add_f32_e32 v213, v39, v213
	ds_read_b64_tr_b16 v[126:127], v233 offset:3584
	v_mfma_f32_32x32x16_bf16 v[80:95], v[188:191], v[112:115], v[80:95]
	v_exp_f32_e32 v72, v72
	v_add_f32_e32 v213, v40, v213
	ds_read_b64_tr_b16 v[144:145], v233 offset:4096
	v_exp_f32_e32 v73, v73
	v_add_f32_e32 v213, v41, v213
	ds_read_b64_tr_b16 v[146:147], v233 offset:4608
	v_mfma_f32_32x32x16_bf16 v[48:63], v[184:187], v[112:115], v[48:63]
	v_exp_f32_e32 v74, v74
	v_add_f32_e32 v213, v42, v213
	ds_read_b64_tr_b16 v[136:137], v233 offset:5120
	v_exp_f32_e32 v75, v75
	v_add_f32_e32 v213, v43, v213
	ds_read_b64_tr_b16 v[138:139], v233 offset:5632
	v_mfma_f32_32x32x16_bf16 v[80:95], v[180:183], v[108:111], v[80:95]
	v_exp_f32_e32 v76, v76
	v_add_f32_e32 v213, v44, v213
	ds_read_b64_tr_b16 v[128:129], v233 offset:6144
	v_exp_f32_e32 v77, v77
	v_add_f32_e32 v213, v45, v213
	ds_read_b64_tr_b16 v[130:131], v233 offset:6656
	v_mfma_f32_32x32x16_bf16 v[48:63], v[176:179], v[108:111], v[48:63]
	v_exp_f32_e32 v78, v78
	v_add_f32_e32 v213, v46, v213
	ds_read_b64_tr_b16 v[120:121], v233 offset:7168
	v_exp_f32_e32 v79, v79
	v_add_f32_e32 v213, v47, v213
	ds_read_b64_tr_b16 v[122:123], v233 offset:7680
	v_mfma_f32_32x32x16_bf16 v[80:95], v[172:175], v[104:107], v[80:95]
	v_add_f32_e32 v245, v64, v65
	v_add_f32_e32 v245, v66, v245
	v_add_f32_e32 v245, v67, v245
	v_add_f32_e32 v245, v68, v245
	v_add_f32_e32 v245, v69, v245
	v_add_f32_e32 v245, v70, v245
	v_mfma_f32_32x32x16_bf16 v[48:63], v[168:171], v[104:107], v[48:63]
	v_add_f32_e32 v245, v71, v245
	v_add_f32_e32 v245, v72, v245
	v_add_f32_e32 v245, v73, v245
	v_add_f32_e32 v245, v74, v245
	v_add_f32_e32 v245, v75, v245
	v_mfma_f32_32x32x16_bf16 v[80:95], v[164:167], v[100:103], v[80:95]
	v_add_f32_e32 v245, v76, v245
	v_add_f32_e32 v245, v77, v245
	v_add_f32_e32 v245, v78, v245
	v_add_f32_e32 v245, v79, v245
	v_add_f32_e32 v213, v245, v213
	v_mfma_f32_32x32x16_bf16 v[48:63], v[160:163], v[100:103], v[48:63]
	v_cvt_pk_bf16_f32 v32, v32, v33
	v_cvt_pk_bf16_f32 v33, v34, v35
	v_cvt_pk_bf16_f32 v34, v36, v37
	v_cvt_pk_bf16_f32 v35, v38, v39
	v_cvt_pk_bf16_f32 v36, v40, v41
	v_cvt_pk_bf16_f32 v37, v42, v43
	v_mfma_f32_32x32x16_bf16 v[80:95], v[156:159], v[96:99], v[80:95]
	v_cvt_pk_bf16_f32 v38, v44, v45
	v_cvt_pk_bf16_f32 v39, v46, v47
	v_cvt_pk_bf16_f32 v64, v64, v65
	v_cvt_pk_bf16_f32 v65, v66, v67
	v_cvt_pk_bf16_f32 v66, v68, v69
	v_cvt_pk_bf16_f32 v67, v70, v71
	v_mfma_f32_32x32x16_bf16 v[48:63], v[152:155], v[96:99], v[48:63]
	v_cvt_pk_bf16_f32 v68, v72, v73
	v_cvt_pk_bf16_f32 v69, v74, v75
	v_cvt_pk_bf16_f32 v70, v76, v77
	v_cvt_pk_bf16_f32 v71, v78, v79
	s_waitcnt lgkmcnt(0)
	v_mfma_f32_32x32x16_bf16 v[0:15], v[32:35], v[148:151], v[0:15]
	v_exp_f32_e32 v40, v88
	v_exp_f32_e32 v41, v89
	v_mfma_f32_32x32x16_bf16 v[16:31], v[32:35], v[144:147], v[16:31]
	v_exp_f32_e32 v42, v90
	v_exp_f32_e32 v43, v91
	v_mfma_f32_32x32x16_bf16 v[0:15], v[36:39], v[140:143], v[0:15]
	v_exp_f32_e32 v44, v92
	v_exp_f32_e32 v45, v93
	v_mfma_f32_32x32x16_bf16 v[16:31], v[36:39], v[136:139], v[16:31]
	v_exp_f32_e32 v46, v94
	v_exp_f32_e32 v47, v95
	v_mfma_f32_32x32x16_bf16 v[0:15], v[64:67], v[132:135], v[0:15]
	v_exp_f32_e32 v32, v80
	v_exp_f32_e32 v33, v81
	v_mfma_f32_32x32x16_bf16 v[16:31], v[64:67], v[128:131], v[16:31]
	v_exp_f32_e32 v34, v82
	v_exp_f32_e32 v35, v83
	v_mfma_f32_32x32x16_bf16 v[0:15], v[68:71], v[124:127], v[0:15]
	v_exp_f32_e32 v36, v84
	v_exp_f32_e32 v37, v85
	v_mfma_f32_32x32x16_bf16 v[16:31], v[68:71], v[120:123], v[16:31]
	v_exp_f32_e32 v38, v86
	v_exp_f32_e32 v39, v87
	s_setprio 0
	s_barrier
	s_and_b64 vcc, exec, s[4:5]
	s_cbranch_vccnz .LBB0_603
	s_barrier
